# residual-add epilogues of the N=2048 GEMMs (P4,P7,P9): residual tiles prefetched through a small register ring instead of one wait per chunk
# speedup vs baseline: 1.0289x; 1.0040x over previous
.LBB0_566:
	s_add_i32 s8, s58, 0xffffe000
	s_ashr_i32 s59, s58, 31
	s_cmpk_lt_i32 s58, 0x2000
	s_cselect_b32 s13, s59, 0
	s_cselect_b32 s12, s58, s8
	s_waitcnt lgkmcnt(0)
	s_cselect_b32 s8, s5, s7
	s_cselect_b32 s41, s4, s6
	s_lshl_b64 s[12:13], s[12:13], 13
	v_lshl_add_u32 v148, v166, 3, s84
	s_add_u32 s60, s41, s12
	v_ashrrev_i32_e32 v149, 31, v148
	v_lshlrev_b64 v[156:157], 11, v[156:157]
	s_addc_u32 s61, s8, s13
	v_lshl_add_u64 v[156:157], v[156:157], 0, v[148:149]
	s_ashr_i32 s51, s50, 31
	v_lshl_add_u64 v[156:157], v[156:157], 0, s[50:51]
	v_lshl_add_u64 v[174:175], v[156:157], 2, s[60:61]
	global_load_dwordx4 v[166:169], v[174:175], off
	global_load_dwordx4 v[170:173], v[174:175], off offset:16
	s_lshl_b64 s[12:13], s[58:59], 12
	s_add_u32 s58, s75, s12
	s_addc_u32 s59, s76, s13
	v_lshl_add_u64 v[156:157], v[156:157], 1, s[58:59]
	v_ashrrev_i32_e32 v155, 31, v154
	v_lshlrev_b64 v[154:155], 11, v[154:155]
	v_lshl_add_u64 v[154:155], v[154:155], 0, v[148:149]
	v_lshl_add_u64 v[154:155], v[154:155], 0, s[50:51]
	v_ashrrev_i32_e32 v153, 31, v152
	v_ashrrev_i32_e32 v151, 31, v150
	v_ashrrev_i32_e32 v147, 31, v146
	v_ashrrev_i32_e32 v145, 31, v144
	v_ashrrev_i32_e32 v143, 31, v142
	v_ashrrev_i32_e32 v141, 31, v140
	global_load_dwordx4 v[184:187], v[174:175], off offset:512
	global_load_dwordx4 v[188:191], v[174:175], off offset:528
	v_lshl_add_u64 v[208:209], v[154:155], 2, s[60:61]
	global_load_dwordx4 v[192:195], v[208:209], off
	global_load_dwordx4 v[196:199], v[208:209], off offset:16
	v_lshl_add_u64 v[208:209], v[154:155], 2, s[60:61]
	global_load_dwordx4 v[200:203], v[208:209], off offset:512
	global_load_dwordx4 v[204:207], v[208:209], off offset:528
	s_waitcnt vmcnt(6)
	v_lshlrev_b64 v[208:209], 11, v[152:153]
	v_lshl_add_u64 v[210:211], v[208:209], 0, v[148:149]
	v_lshl_add_u64 v[212:213], v[210:211], 0, s[50:51]
	v_lshl_add_u64 v[214:215], v[212:213], 2, s[60:61]
	global_load_dwordx4 v[176:179], v[214:215], off
	global_load_dwordx4 v[180:183], v[214:215], off offset:16
	v_pk_add_f32 v[124:125], v[124:125], v[166:167]
	v_pk_add_f32 v[166:167], v[122:123], v[172:173]
	v_pk_add_f32 v[122:123], v[120:121], v[170:171]
	v_pk_add_f32 v[126:127], v[126:127], v[168:169]
	v_cvt_pk_bf16_f32 v120, v124, v125
	s_nop 0
	v_cvt_pk_bf16_f32 v121, v126, v127
	v_cvt_pk_bf16_f32 v122, v122, v123
	v_cvt_pk_bf16_f32 v123, v166, v167
	flat_store_dwordx4 v[156:157], v[120:123]
	s_nop 0
	v_lshl_add_u64 v[166:167], v[154:155], 2, s[60:61]
	s_waitcnt vmcnt(7)
	s_nop 1
	v_mov_b32_e32 v120, v184
	v_mov_b32_e32 v121, v185
	v_mov_b32_e32 v122, v186
	v_mov_b32_e32 v123, v187
	v_mov_b32_e32 v124, v188
	v_mov_b32_e32 v125, v189
	v_mov_b32_e32 v126, v190
	v_mov_b32_e32 v127, v191
	v_lshlrev_b64 v[208:209], 11, v[152:153]
	v_lshl_add_u64 v[210:211], v[208:209], 0, v[148:149]
	v_lshl_add_u64 v[212:213], v[210:211], 0, s[50:51]
	v_lshl_add_u64 v[214:215], v[212:213], 2, s[60:61]
	global_load_dwordx4 v[184:187], v[214:215], off offset:512
	global_load_dwordx4 v[188:191], v[214:215], off offset:528
	v_pk_add_f32 v[116:117], v[116:117], v[120:121]
	v_pk_add_f32 v[120:121], v[114:115], v[126:127]
	v_pk_add_f32 v[114:115], v[112:113], v[124:125]
	v_pk_add_f32 v[118:119], v[118:119], v[122:123]
	v_cvt_pk_bf16_f32 v112, v116, v117
	s_nop 0
	v_cvt_pk_bf16_f32 v113, v118, v119
	v_cvt_pk_bf16_f32 v114, v114, v115
	v_cvt_pk_bf16_f32 v115, v120, v121
	flat_store_dwordx4 v[156:157], v[112:115] offset:256
	s_nop 0
	v_lshl_add_u64 v[120:121], v[154:155], 1, s[58:59]
	s_waitcnt vmcnt(8)
	s_nop 1
	v_mov_b32_e32 v112, v192
	v_mov_b32_e32 v113, v193
	v_mov_b32_e32 v114, v194
	v_mov_b32_e32 v115, v195
	v_mov_b32_e32 v116, v196
	v_mov_b32_e32 v117, v197
	v_mov_b32_e32 v118, v198
	v_mov_b32_e32 v119, v199
	v_lshlrev_b64 v[208:209], 11, v[150:151]
	v_lshl_add_u64 v[210:211], v[208:209], 0, v[148:149]
	v_lshl_add_u64 v[212:213], v[210:211], 0, s[50:51]
	v_lshl_add_u64 v[214:215], v[212:213], 2, s[60:61]
	global_load_dwordx4 v[192:195], v[214:215], off
	global_load_dwordx4 v[196:199], v[214:215], off offset:16
	v_pk_add_f32 v[108:109], v[108:109], v[112:113]
	v_pk_add_f32 v[112:113], v[106:107], v[118:119]
	v_pk_add_f32 v[106:107], v[104:105], v[116:117]
	v_pk_add_f32 v[110:111], v[110:111], v[114:115]
	v_cvt_pk_bf16_f32 v104, v108, v109
	s_nop 0
	v_cvt_pk_bf16_f32 v105, v110, v111
	v_cvt_pk_bf16_f32 v106, v106, v107
	v_cvt_pk_bf16_f32 v107, v112, v113
	flat_store_dwordx4 v[120:121], v[104:107]
	s_nop 0
	v_lshlrev_b64 v[112:113], 11, v[152:153]
	v_lshl_add_u64 v[112:113], v[112:113], 0, v[148:149]
	v_lshl_add_u64 v[112:113], v[112:113], 0, s[50:51]
	v_lshl_add_u64 v[114:115], v[112:113], 2, s[60:61]
	s_waitcnt vmcnt(9)
	s_nop 1
	v_mov_b32_e32 v104, v200
	v_mov_b32_e32 v105, v201
	v_mov_b32_e32 v106, v202
	v_mov_b32_e32 v107, v203
	v_mov_b32_e32 v108, v204
	v_mov_b32_e32 v109, v205
	v_mov_b32_e32 v110, v206
	v_mov_b32_e32 v111, v207
	v_lshlrev_b64 v[208:209], 11, v[150:151]
	v_lshl_add_u64 v[210:211], v[208:209], 0, v[148:149]
	v_lshl_add_u64 v[212:213], v[210:211], 0, s[50:51]
	v_lshl_add_u64 v[214:215], v[212:213], 2, s[60:61]
	global_load_dwordx4 v[200:203], v[214:215], off offset:512
	global_load_dwordx4 v[204:207], v[214:215], off offset:528
	v_pk_add_f32 v[100:101], v[100:101], v[104:105]
	v_pk_add_f32 v[104:105], v[98:99], v[110:111]
	v_pk_add_f32 v[98:99], v[96:97], v[108:109]
	v_pk_add_f32 v[102:103], v[102:103], v[106:107]
	v_cvt_pk_bf16_f32 v96, v100, v101
	s_nop 0
	v_cvt_pk_bf16_f32 v97, v102, v103
	v_cvt_pk_bf16_f32 v98, v98, v99
	v_cvt_pk_bf16_f32 v99, v104, v105
	flat_store_dwordx4 v[120:121], v[96:99] offset:256
	s_nop 0
	v_lshl_add_u64 v[104:105], v[112:113], 1, s[58:59]
	s_waitcnt vmcnt(10)
	s_nop 1
	v_mov_b32_e32 v96, v176
	v_mov_b32_e32 v97, v177
	v_mov_b32_e32 v98, v178
	v_mov_b32_e32 v99, v179
	v_mov_b32_e32 v100, v180
	v_mov_b32_e32 v101, v181
	v_mov_b32_e32 v102, v182
	v_mov_b32_e32 v103, v183
	v_lshlrev_b64 v[208:209], 11, v[146:147]
	v_lshl_add_u64 v[210:211], v[208:209], 0, v[148:149]
	v_lshl_add_u64 v[212:213], v[210:211], 0, s[50:51]
	v_lshl_add_u64 v[214:215], v[212:213], 2, s[60:61]
	global_load_dwordx4 v[176:179], v[214:215], off
	global_load_dwordx4 v[180:183], v[214:215], off offset:16
	v_pk_add_f32 v[92:93], v[92:93], v[96:97]
	v_pk_add_f32 v[96:97], v[90:91], v[102:103]
	v_pk_add_f32 v[90:91], v[88:89], v[100:101]
	v_pk_add_f32 v[94:95], v[94:95], v[98:99]
	v_cvt_pk_bf16_f32 v88, v92, v93
	s_nop 0
	v_cvt_pk_bf16_f32 v89, v94, v95
	v_cvt_pk_bf16_f32 v90, v90, v91
	v_cvt_pk_bf16_f32 v91, v96, v97
	flat_store_dwordx4 v[104:105], v[88:91]
	s_nop 0
	v_lshlrev_b64 v[96:97], 11, v[150:151]
	v_lshl_add_u64 v[96:97], v[96:97], 0, v[148:149]
	v_lshl_add_u64 v[96:97], v[96:97], 0, s[50:51]
	v_lshl_add_u64 v[98:99], v[96:97], 2, s[60:61]
	s_waitcnt vmcnt(10)
	s_nop 1
	v_mov_b32_e32 v88, v184
	v_mov_b32_e32 v89, v185
	v_mov_b32_e32 v90, v186
	v_mov_b32_e32 v91, v187
	v_mov_b32_e32 v92, v188
	v_mov_b32_e32 v93, v189
	v_mov_b32_e32 v94, v190
	v_mov_b32_e32 v95, v191
	v_lshlrev_b64 v[208:209], 11, v[146:147]
	v_lshl_add_u64 v[210:211], v[208:209], 0, v[148:149]
	v_lshl_add_u64 v[212:213], v[210:211], 0, s[50:51]
	v_lshl_add_u64 v[214:215], v[212:213], 2, s[60:61]
	global_load_dwordx4 v[184:187], v[214:215], off offset:512
	global_load_dwordx4 v[188:191], v[214:215], off offset:528
	v_pk_add_f32 v[84:85], v[84:85], v[88:89]
	v_pk_add_f32 v[88:89], v[82:83], v[94:95]
	v_pk_add_f32 v[82:83], v[80:81], v[92:93]
	v_pk_add_f32 v[86:87], v[86:87], v[90:91]
	v_cvt_pk_bf16_f32 v80, v84, v85
	s_nop 0
	v_cvt_pk_bf16_f32 v81, v86, v87
	v_cvt_pk_bf16_f32 v82, v82, v83
	v_cvt_pk_bf16_f32 v83, v88, v89
	flat_store_dwordx4 v[104:105], v[80:83] offset:256
	s_nop 0
	v_lshl_add_u64 v[88:89], v[96:97], 1, s[58:59]
	s_waitcnt vmcnt(10)
	s_nop 1
	v_mov_b32_e32 v80, v192
	v_mov_b32_e32 v81, v193
	v_mov_b32_e32 v82, v194
	v_mov_b32_e32 v83, v195
	v_mov_b32_e32 v84, v196
	v_mov_b32_e32 v85, v197
	v_mov_b32_e32 v86, v198
	v_mov_b32_e32 v87, v199
	v_lshlrev_b64 v[208:209], 11, v[144:145]
	v_lshl_add_u64 v[210:211], v[208:209], 0, v[148:149]
	v_lshl_add_u64 v[212:213], v[210:211], 0, s[50:51]
	v_lshl_add_u64 v[214:215], v[212:213], 2, s[60:61]
	global_load_dwordx4 v[192:195], v[214:215], off
	global_load_dwordx4 v[196:199], v[214:215], off offset:16
	v_pk_add_f32 v[76:77], v[76:77], v[80:81]
	v_pk_add_f32 v[80:81], v[74:75], v[86:87]
	v_pk_add_f32 v[74:75], v[72:73], v[84:85]
	v_pk_add_f32 v[78:79], v[78:79], v[82:83]
	v_cvt_pk_bf16_f32 v72, v76, v77
	s_nop 0
	v_cvt_pk_bf16_f32 v73, v78, v79
	v_cvt_pk_bf16_f32 v74, v74, v75
	v_cvt_pk_bf16_f32 v75, v80, v81
	flat_store_dwordx4 v[88:89], v[72:75]
	s_nop 0
	v_lshlrev_b64 v[80:81], 11, v[146:147]
	v_lshl_add_u64 v[80:81], v[80:81], 0, v[148:149]
	v_lshl_add_u64 v[80:81], v[80:81], 0, s[50:51]
	v_lshl_add_u64 v[82:83], v[80:81], 2, s[60:61]
	s_waitcnt vmcnt(10)
	s_nop 1
	v_mov_b32_e32 v72, v200
	v_mov_b32_e32 v73, v201
	v_mov_b32_e32 v74, v202
	v_mov_b32_e32 v75, v203
	v_mov_b32_e32 v76, v204
	v_mov_b32_e32 v77, v205
	v_mov_b32_e32 v78, v206
	v_mov_b32_e32 v79, v207
	v_lshlrev_b64 v[208:209], 11, v[144:145]
	v_lshl_add_u64 v[210:211], v[208:209], 0, v[148:149]
	v_lshl_add_u64 v[212:213], v[210:211], 0, s[50:51]
	v_lshl_add_u64 v[214:215], v[212:213], 2, s[60:61]
	global_load_dwordx4 v[200:203], v[214:215], off offset:512
	global_load_dwordx4 v[204:207], v[214:215], off offset:528
	v_pk_add_f32 v[68:69], v[68:69], v[72:73]
	v_pk_add_f32 v[72:73], v[66:67], v[78:79]
	v_pk_add_f32 v[66:67], v[64:65], v[76:77]
	v_pk_add_f32 v[70:71], v[70:71], v[74:75]
	v_cvt_pk_bf16_f32 v64, v68, v69
	s_nop 0
	v_cvt_pk_bf16_f32 v65, v70, v71
	v_cvt_pk_bf16_f32 v66, v66, v67
	v_cvt_pk_bf16_f32 v67, v72, v73
	flat_store_dwordx4 v[88:89], v[64:67] offset:256
	s_nop 0
	v_lshl_add_u64 v[72:73], v[80:81], 1, s[58:59]
	s_waitcnt vmcnt(10)
	s_nop 1
	v_mov_b32_e32 v64, v176
	v_mov_b32_e32 v65, v177
	v_mov_b32_e32 v66, v178
	v_mov_b32_e32 v67, v179
	v_mov_b32_e32 v68, v180
	v_mov_b32_e32 v69, v181
	v_mov_b32_e32 v70, v182
	v_mov_b32_e32 v71, v183
	v_lshlrev_b64 v[208:209], 11, v[142:143]
	v_lshl_add_u64 v[210:211], v[208:209], 0, v[148:149]
	v_lshl_add_u64 v[212:213], v[210:211], 0, s[50:51]
	v_lshl_add_u64 v[214:215], v[212:213], 2, s[60:61]
	global_load_dwordx4 v[176:179], v[214:215], off
	global_load_dwordx4 v[180:183], v[214:215], off offset:16
	v_pk_add_f32 v[60:61], v[60:61], v[64:65]
	v_pk_add_f32 v[64:65], v[58:59], v[70:71]
	v_pk_add_f32 v[58:59], v[56:57], v[68:69]
	v_pk_add_f32 v[62:63], v[62:63], v[66:67]
	v_cvt_pk_bf16_f32 v56, v60, v61
	s_nop 0
	v_cvt_pk_bf16_f32 v57, v62, v63
	v_cvt_pk_bf16_f32 v58, v58, v59
	v_cvt_pk_bf16_f32 v59, v64, v65
	flat_store_dwordx4 v[72:73], v[56:59]
	s_nop 0
	v_lshlrev_b64 v[64:65], 11, v[144:145]
	v_lshl_add_u64 v[64:65], v[64:65], 0, v[148:149]
	v_lshl_add_u64 v[64:65], v[64:65], 0, s[50:51]
	v_lshl_add_u64 v[66:67], v[64:65], 2, s[60:61]
	s_waitcnt vmcnt(10)
	s_nop 1
	v_mov_b32_e32 v56, v184
	v_mov_b32_e32 v57, v185
	v_mov_b32_e32 v58, v186
	v_mov_b32_e32 v59, v187
	v_mov_b32_e32 v60, v188
	v_mov_b32_e32 v61, v189
	v_mov_b32_e32 v62, v190
	v_mov_b32_e32 v63, v191
	v_lshlrev_b64 v[208:209], 11, v[142:143]
	v_lshl_add_u64 v[210:211], v[208:209], 0, v[148:149]
	v_lshl_add_u64 v[212:213], v[210:211], 0, s[50:51]
	v_lshl_add_u64 v[214:215], v[212:213], 2, s[60:61]
	global_load_dwordx4 v[184:187], v[214:215], off offset:512
	global_load_dwordx4 v[188:191], v[214:215], off offset:528
	v_pk_add_f32 v[52:53], v[52:53], v[56:57]
	v_pk_add_f32 v[56:57], v[50:51], v[62:63]
	v_pk_add_f32 v[50:51], v[48:49], v[60:61]
	v_pk_add_f32 v[54:55], v[54:55], v[58:59]
	v_cvt_pk_bf16_f32 v48, v52, v53
	s_nop 0
	v_cvt_pk_bf16_f32 v49, v54, v55
	v_cvt_pk_bf16_f32 v50, v50, v51
	v_cvt_pk_bf16_f32 v51, v56, v57
	flat_store_dwordx4 v[72:73], v[48:51] offset:256
	s_nop 0
	v_lshl_add_u64 v[56:57], v[64:65], 1, s[58:59]
	s_waitcnt vmcnt(10)
	s_nop 1
	v_mov_b32_e32 v48, v192
	v_mov_b32_e32 v49, v193
	v_mov_b32_e32 v50, v194
	v_mov_b32_e32 v51, v195
	v_mov_b32_e32 v52, v196
	v_mov_b32_e32 v53, v197
	v_mov_b32_e32 v54, v198
	v_mov_b32_e32 v55, v199
	v_lshlrev_b64 v[208:209], 11, v[140:141]
	v_lshl_add_u64 v[210:211], v[208:209], 0, v[148:149]
	v_lshl_add_u64 v[212:213], v[210:211], 0, s[50:51]
	v_lshl_add_u64 v[214:215], v[212:213], 2, s[60:61]
	global_load_dwordx4 v[192:195], v[214:215], off
	global_load_dwordx4 v[196:199], v[214:215], off offset:16
	v_pk_add_f32 v[44:45], v[44:45], v[48:49]
	v_pk_add_f32 v[48:49], v[42:43], v[54:55]
	v_pk_add_f32 v[42:43], v[40:41], v[52:53]
	v_pk_add_f32 v[46:47], v[46:47], v[50:51]
	v_cvt_pk_bf16_f32 v40, v44, v45
	s_nop 0
	v_cvt_pk_bf16_f32 v41, v46, v47
	v_cvt_pk_bf16_f32 v42, v42, v43
	v_cvt_pk_bf16_f32 v43, v48, v49
	flat_store_dwordx4 v[56:57], v[40:43]
	s_nop 0
	v_lshlrev_b64 v[48:49], 11, v[142:143]
	v_lshl_add_u64 v[48:49], v[48:49], 0, v[148:149]
	v_lshl_add_u64 v[48:49], v[48:49], 0, s[50:51]
	v_lshl_add_u64 v[50:51], v[48:49], 2, s[60:61]
	s_waitcnt vmcnt(10)
	s_nop 1
	v_mov_b32_e32 v40, v200
	v_mov_b32_e32 v41, v201
	v_mov_b32_e32 v42, v202
	v_mov_b32_e32 v43, v203
	v_mov_b32_e32 v44, v204
	v_mov_b32_e32 v45, v205
	v_mov_b32_e32 v46, v206
	v_mov_b32_e32 v47, v207
	v_lshlrev_b64 v[208:209], 11, v[140:141]
	v_lshl_add_u64 v[210:211], v[208:209], 0, v[148:149]
	v_lshl_add_u64 v[212:213], v[210:211], 0, s[50:51]
	v_lshl_add_u64 v[214:215], v[212:213], 2, s[60:61]
	global_load_dwordx4 v[200:203], v[214:215], off offset:512
	global_load_dwordx4 v[204:207], v[214:215], off offset:528
	v_pk_add_f32 v[36:37], v[36:37], v[40:41]
	v_pk_add_f32 v[40:41], v[34:35], v[46:47]
	v_pk_add_f32 v[34:35], v[32:33], v[44:45]
	v_pk_add_f32 v[38:39], v[38:39], v[42:43]
	v_cvt_pk_bf16_f32 v32, v36, v37
	s_nop 0
	v_cvt_pk_bf16_f32 v33, v38, v39
	v_cvt_pk_bf16_f32 v34, v34, v35
	v_cvt_pk_bf16_f32 v35, v40, v41
	flat_store_dwordx4 v[56:57], v[32:35] offset:256
	s_nop 0
	v_lshl_add_u64 v[40:41], v[48:49], 1, s[58:59]
	s_waitcnt vmcnt(10)
	s_nop 1
	v_mov_b32_e32 v32, v176
	v_mov_b32_e32 v33, v177
	v_mov_b32_e32 v34, v178
	v_mov_b32_e32 v35, v179
	v_mov_b32_e32 v36, v180
	v_mov_b32_e32 v37, v181
	v_mov_b32_e32 v38, v182
	v_mov_b32_e32 v39, v183
	v_pk_add_f32 v[28:29], v[28:29], v[32:33]
	v_pk_add_f32 v[32:33], v[26:27], v[38:39]
	v_pk_add_f32 v[26:27], v[24:25], v[36:37]
	v_pk_add_f32 v[30:31], v[30:31], v[34:35]
	v_cvt_pk_bf16_f32 v24, v28, v29
	s_nop 0
	v_cvt_pk_bf16_f32 v25, v30, v31
	v_cvt_pk_bf16_f32 v26, v26, v27
	v_cvt_pk_bf16_f32 v27, v32, v33
	flat_store_dwordx4 v[40:41], v[24:27]
	s_nop 0
	v_lshlrev_b64 v[32:33], 11, v[140:141]
	v_lshl_add_u64 v[32:33], v[32:33], 0, v[148:149]
	v_lshl_add_u64 v[32:33], v[32:33], 0, s[50:51]
	v_lshl_add_u64 v[34:35], v[32:33], 2, s[60:61]
	s_waitcnt vmcnt(8)
	s_nop 1
	v_mov_b32_e32 v24, v184
	v_mov_b32_e32 v25, v185
	v_mov_b32_e32 v26, v186
	v_mov_b32_e32 v27, v187
	v_mov_b32_e32 v28, v188
	v_mov_b32_e32 v29, v189
	v_mov_b32_e32 v30, v190
	v_mov_b32_e32 v31, v191
	v_pk_add_f32 v[20:21], v[20:21], v[24:25]
	v_pk_add_f32 v[24:25], v[18:19], v[30:31]
	v_pk_add_f32 v[18:19], v[16:17], v[28:29]
	v_pk_add_f32 v[22:23], v[22:23], v[26:27]
	v_cvt_pk_bf16_f32 v16, v20, v21
	s_nop 0
	v_cvt_pk_bf16_f32 v17, v22, v23
	v_cvt_pk_bf16_f32 v18, v18, v19
	v_cvt_pk_bf16_f32 v19, v24, v25
	flat_store_dwordx4 v[40:41], v[16:19] offset:256
	s_nop 0
	v_lshl_add_u64 v[24:25], v[32:33], 1, s[58:59]
	s_waitcnt vmcnt(6)
	s_nop 1
	v_mov_b32_e32 v16, v192
	v_mov_b32_e32 v17, v193
	v_mov_b32_e32 v18, v194
	v_mov_b32_e32 v19, v195
	v_mov_b32_e32 v20, v196
	v_mov_b32_e32 v21, v197
	v_mov_b32_e32 v22, v198
	v_mov_b32_e32 v23, v199
	v_pk_add_f32 v[12:13], v[12:13], v[16:17]
	v_pk_add_f32 v[16:17], v[10:11], v[22:23]
	v_pk_add_f32 v[10:11], v[8:9], v[20:21]
	v_pk_add_f32 v[14:15], v[14:15], v[18:19]
	v_cvt_pk_bf16_f32 v8, v12, v13
	s_nop 0
	v_cvt_pk_bf16_f32 v9, v14, v15
	v_cvt_pk_bf16_f32 v10, v10, v11
	v_cvt_pk_bf16_f32 v11, v16, v17
	flat_store_dwordx4 v[24:25], v[8:11]
	s_nop 0
	s_waitcnt vmcnt(4)
	s_nop 1
	v_mov_b32_e32 v8, v200
	v_mov_b32_e32 v9, v201
	v_mov_b32_e32 v10, v202
	v_mov_b32_e32 v11, v203
	v_mov_b32_e32 v12, v204
	v_mov_b32_e32 v13, v205
	v_mov_b32_e32 v14, v206
	v_mov_b32_e32 v15, v207
	v_pk_add_f32 v[4:5], v[4:5], v[8:9]
	v_pk_add_f32 v[8:9], v[2:3], v[14:15]
	v_pk_add_f32 v[2:3], v[0:1], v[12:13]
	v_pk_add_f32 v[6:7], v[6:7], v[10:11]
	v_cvt_pk_bf16_f32 v0, v4, v5
	s_nop 0
	v_cvt_pk_bf16_f32 v1, v6, v7
	v_cvt_pk_bf16_f32 v2, v2, v3
	v_cvt_pk_bf16_f32 v3, v8, v9
	flat_store_dwordx4 v[24:25], v[0:3] offset:256

.LBB0_962:
	v_lshl_add_u32 v146, v165, 3, s81
	v_ashrrev_i32_e32 v147, 31, v146
	v_lshlrev_b64 v[156:157], 11, v[156:157]
	s_ashr_i32 s55, s54, 31
	v_lshl_add_u64 v[156:157], v[156:157], 0, v[146:147]
	s_lshl_b64 s[56:57], s[54:55], 12
	v_lshl_add_u64 v[156:157], v[156:157], 0, s[46:47]
	s_add_u32 s54, s71, s56
	s_addc_u32 s55, s72, s57
	v_lshlrev_b64 v[156:157], 1, v[156:157]
	v_lshl_add_u64 v[170:171], s[54:55], 0, v[156:157]
	flat_load_dwordx4 v[166:169], v[170:171]
	v_ashrrev_i32_e32 v155, 31, v154
	s_add_u32 s56, s73, s56
	v_lshlrev_b64 v[154:155], 11, v[154:155]
	s_addc_u32 s57, s74, s57
	v_lshl_add_u64 v[154:155], v[154:155], 0, v[146:147]
	v_lshl_add_u64 v[156:157], s[56:57], 0, v[156:157]
	v_lshl_add_u64 v[154:155], v[154:155], 0, s[46:47]
	v_lshlrev_b64 v[154:155], 1, v[154:155]
	v_ashrrev_i32_e32 v153, 31, v152
	v_ashrrev_i32_e32 v151, 31, v150
	v_ashrrev_i32_e32 v149, 31, v148
	v_ashrrev_i32_e32 v145, 31, v144
	v_ashrrev_i32_e32 v143, 31, v142
	v_ashrrev_i32_e32 v141, 31, v140
	global_load_dwordx4 v[232:235], v[170:171], off offset:256
	v_lshl_add_u64 v[198:199], s[54:55], 0, v[154:155]
	global_load_dwordx4 v[236:239], v[198:199], off
	v_lshl_add_u64 v[198:199], s[54:55], 0, v[154:155]
	global_load_dwordx4 v[240:243], v[198:199], off offset:256
	v_lshlrev_b64 v[198:199], 11, v[152:153]
	v_lshl_add_u64 v[200:201], v[198:199], 0, v[146:147]
	v_lshl_add_u64 v[202:203], v[200:201], 0, s[46:47]
	v_lshlrev_b64 v[204:205], 1, v[202:203]
	v_lshl_add_u64 v[206:207], s[54:55], 0, v[204:205]
	global_load_dwordx4 v[244:247], v[206:207], off
	v_lshlrev_b64 v[198:199], 11, v[152:153]
	v_lshl_add_u64 v[200:201], v[198:199], 0, v[146:147]
	v_lshl_add_u64 v[202:203], v[200:201], 0, s[46:47]
	v_lshlrev_b64 v[204:205], 1, v[202:203]
	v_lshl_add_u64 v[206:207], s[54:55], 0, v[204:205]
	global_load_dwordx4 v[248:251], v[206:207], off offset:256
	v_lshlrev_b64 v[198:199], 11, v[150:151]
	v_lshl_add_u64 v[200:201], v[198:199], 0, v[146:147]
	v_lshl_add_u64 v[202:203], v[200:201], 0, s[46:47]
	v_lshlrev_b64 v[204:205], 1, v[202:203]
	v_lshl_add_u64 v[206:207], s[54:55], 0, v[204:205]
	global_load_dwordx4 v[252:255], v[206:207], off
	s_waitcnt vmcnt(6) lgkmcnt(0)
	v_lshlrev_b64 v[198:199], 11, v[150:151]
	v_lshl_add_u64 v[200:201], v[198:199], 0, v[146:147]
	v_lshl_add_u64 v[202:203], v[200:201], 0, s[46:47]
	v_lshlrev_b64 v[204:205], 1, v[202:203]
	v_lshl_add_u64 v[206:207], s[54:55], 0, v[204:205]
	global_load_dwordx4 v[228:231], v[206:207], off offset:256
	v_lshlrev_b32_e32 v172, 16, v166
	v_and_b32_e32 v173, 0xffff0000, v166
	v_lshlrev_b32_e32 v166, 16, v167
	v_and_b32_e32 v167, 0xffff0000, v167
	v_lshlrev_b32_e32 v174, 16, v168
	v_and_b32_e32 v175, 0xffff0000, v168
	v_lshlrev_b32_e32 v168, 16, v169
	v_and_b32_e32 v169, 0xffff0000, v169
	v_pk_add_f32 v[126:127], v[126:127], v[166:167]
	v_pk_add_f32 v[124:125], v[124:125], v[172:173]
	v_pk_add_f32 v[166:167], v[122:123], v[168:169]
	v_pk_add_f32 v[122:123], v[120:121], v[174:175]
	v_cvt_pk_bf16_f32 v120, v124, v125
	v_cvt_pk_bf16_f32 v121, v126, v127
	s_nop 0
	v_cvt_pk_bf16_f32 v122, v122, v123
	v_cvt_pk_bf16_f32 v123, v166, v167
	v_lshl_add_u64 v[166:167], s[54:55], 0, v[154:155]
	flat_store_dwordx4 v[156:157], v[120:123]
	s_waitcnt vmcnt(7) lgkmcnt(0)
	s_nop 1
	v_mov_b32_e32 v124, v232
	v_mov_b32_e32 v125, v233
	v_mov_b32_e32 v126, v234
	v_mov_b32_e32 v127, v235
	v_lshlrev_b64 v[198:199], 11, v[148:149]
	v_lshl_add_u64 v[200:201], v[198:199], 0, v[146:147]
	v_lshl_add_u64 v[202:203], v[200:201], 0, s[46:47]
	v_lshlrev_b64 v[204:205], 1, v[202:203]
	v_lshl_add_u64 v[206:207], s[54:55], 0, v[204:205]
	global_load_dwordx4 v[232:235], v[206:207], off
	s_nop 0
	v_lshlrev_b32_e32 v120, 16, v124
	v_and_b32_e32 v121, 0xffff0000, v124
	v_lshlrev_b32_e32 v122, 16, v125
	v_and_b32_e32 v123, 0xffff0000, v125
	v_lshlrev_b32_e32 v124, 16, v126
	v_and_b32_e32 v125, 0xffff0000, v126
	v_lshlrev_b32_e32 v126, 16, v127
	v_and_b32_e32 v127, 0xffff0000, v127
	v_pk_add_f32 v[116:117], v[116:117], v[120:121]
	v_pk_add_f32 v[120:121], v[114:115], v[126:127]
	v_pk_add_f32 v[114:115], v[112:113], v[124:125]
	v_pk_add_f32 v[118:119], v[118:119], v[122:123]
	v_cvt_pk_bf16_f32 v112, v116, v117
	s_nop 0
	v_cvt_pk_bf16_f32 v113, v118, v119
	v_cvt_pk_bf16_f32 v114, v114, v115
	v_cvt_pk_bf16_f32 v115, v120, v121
	flat_store_dwordx4 v[156:157], v[112:115] offset:256
	s_waitcnt vmcnt(8) lgkmcnt(0)
	s_nop 1
	v_mov_b32_e32 v112, v236
	v_mov_b32_e32 v113, v237
	v_mov_b32_e32 v114, v238
	v_mov_b32_e32 v115, v239
	v_lshlrev_b64 v[198:199], 11, v[148:149]
	v_lshl_add_u64 v[200:201], v[198:199], 0, v[146:147]
	v_lshl_add_u64 v[202:203], v[200:201], 0, s[46:47]
	v_lshlrev_b64 v[204:205], 1, v[202:203]
	v_lshl_add_u64 v[206:207], s[54:55], 0, v[204:205]
	global_load_dwordx4 v[236:239], v[206:207], off offset:256
	v_lshlrev_b32_e32 v116, 16, v112
	v_and_b32_e32 v117, 0xffff0000, v112
	v_lshlrev_b32_e32 v112, 16, v113
	v_and_b32_e32 v113, 0xffff0000, v113
	v_lshlrev_b32_e32 v118, 16, v114
	v_and_b32_e32 v119, 0xffff0000, v114
	v_lshlrev_b32_e32 v114, 16, v115
	v_and_b32_e32 v115, 0xffff0000, v115
	v_pk_add_f32 v[110:111], v[110:111], v[112:113]
	v_pk_add_f32 v[108:109], v[108:109], v[116:117]
	v_pk_add_f32 v[112:113], v[106:107], v[114:115]
	v_pk_add_f32 v[106:107], v[104:105], v[118:119]
	v_cvt_pk_bf16_f32 v104, v108, v109
	v_cvt_pk_bf16_f32 v105, v110, v111
	v_lshl_add_u64 v[116:117], s[56:57], 0, v[154:155]
	v_cvt_pk_bf16_f32 v106, v106, v107
	v_cvt_pk_bf16_f32 v107, v112, v113
	v_lshlrev_b64 v[112:113], 11, v[152:153]
	v_lshl_add_u64 v[112:113], v[112:113], 0, v[146:147]
	v_lshl_add_u64 v[112:113], v[112:113], 0, s[46:47]
	flat_store_dwordx4 v[116:117], v[104:107]
	v_lshlrev_b64 v[112:113], 1, v[112:113]
	v_lshl_add_u64 v[114:115], s[54:55], 0, v[112:113]
	s_waitcnt vmcnt(9) lgkmcnt(0)
	s_nop 1
	v_mov_b32_e32 v108, v240
	v_mov_b32_e32 v109, v241
	v_mov_b32_e32 v110, v242
	v_mov_b32_e32 v111, v243
	v_lshlrev_b64 v[198:199], 11, v[144:145]
	v_lshl_add_u64 v[200:201], v[198:199], 0, v[146:147]
	v_lshl_add_u64 v[202:203], v[200:201], 0, s[46:47]
	v_lshlrev_b64 v[204:205], 1, v[202:203]
	v_lshl_add_u64 v[206:207], s[54:55], 0, v[204:205]
	global_load_dwordx4 v[240:243], v[206:207], off
	v_lshlrev_b32_e32 v104, 16, v108
	v_and_b32_e32 v105, 0xffff0000, v108
	v_lshlrev_b32_e32 v106, 16, v109
	v_and_b32_e32 v107, 0xffff0000, v109
	v_lshlrev_b32_e32 v108, 16, v110
	v_and_b32_e32 v109, 0xffff0000, v110
	v_lshlrev_b32_e32 v110, 16, v111
	v_and_b32_e32 v111, 0xffff0000, v111
	v_pk_add_f32 v[100:101], v[100:101], v[104:105]
	v_pk_add_f32 v[104:105], v[98:99], v[110:111]
	v_pk_add_f32 v[98:99], v[96:97], v[108:109]
	v_pk_add_f32 v[102:103], v[102:103], v[106:107]
	v_cvt_pk_bf16_f32 v96, v100, v101
	s_nop 0
	v_cvt_pk_bf16_f32 v97, v102, v103
	v_cvt_pk_bf16_f32 v98, v98, v99
	v_cvt_pk_bf16_f32 v99, v104, v105
	flat_store_dwordx4 v[116:117], v[96:99] offset:256
	s_waitcnt vmcnt(10) lgkmcnt(0)
	s_nop 1
	v_mov_b32_e32 v96, v244
	v_mov_b32_e32 v97, v245
	v_mov_b32_e32 v98, v246
	v_mov_b32_e32 v99, v247
	v_lshlrev_b64 v[198:199], 11, v[144:145]
	v_lshl_add_u64 v[200:201], v[198:199], 0, v[146:147]
	v_lshl_add_u64 v[202:203], v[200:201], 0, s[46:47]
	v_lshlrev_b64 v[204:205], 1, v[202:203]
	v_lshl_add_u64 v[206:207], s[54:55], 0, v[204:205]
	global_load_dwordx4 v[244:247], v[206:207], off offset:256
	v_lshlrev_b32_e32 v100, 16, v96
	v_and_b32_e32 v101, 0xffff0000, v96
	v_lshlrev_b32_e32 v96, 16, v97
	v_and_b32_e32 v97, 0xffff0000, v97
	v_lshlrev_b32_e32 v102, 16, v98
	v_and_b32_e32 v103, 0xffff0000, v98
	v_lshlrev_b32_e32 v98, 16, v99
	v_and_b32_e32 v99, 0xffff0000, v99
	v_pk_add_f32 v[94:95], v[94:95], v[96:97]
	v_pk_add_f32 v[92:93], v[92:93], v[100:101]
	v_pk_add_f32 v[96:97], v[90:91], v[98:99]
	v_pk_add_f32 v[90:91], v[88:89], v[102:103]
	v_cvt_pk_bf16_f32 v88, v92, v93
	v_cvt_pk_bf16_f32 v89, v94, v95
	v_lshl_add_u64 v[100:101], s[56:57], 0, v[112:113]
	v_cvt_pk_bf16_f32 v90, v90, v91
	v_cvt_pk_bf16_f32 v91, v96, v97
	v_lshlrev_b64 v[96:97], 11, v[150:151]
	v_lshl_add_u64 v[96:97], v[96:97], 0, v[146:147]
	v_lshl_add_u64 v[96:97], v[96:97], 0, s[46:47]
	flat_store_dwordx4 v[100:101], v[88:91]
	v_lshlrev_b64 v[96:97], 1, v[96:97]
	v_lshl_add_u64 v[98:99], s[54:55], 0, v[96:97]
	s_waitcnt vmcnt(11) lgkmcnt(0)
	s_nop 1
	v_mov_b32_e32 v92, v248
	v_mov_b32_e32 v93, v249
	v_mov_b32_e32 v94, v250
	v_mov_b32_e32 v95, v251
	v_lshlrev_b64 v[198:199], 11, v[142:143]
	v_lshl_add_u64 v[200:201], v[198:199], 0, v[146:147]
	v_lshl_add_u64 v[202:203], v[200:201], 0, s[46:47]
	v_lshlrev_b64 v[204:205], 1, v[202:203]
	v_lshl_add_u64 v[206:207], s[54:55], 0, v[204:205]
	global_load_dwordx4 v[248:251], v[206:207], off
	v_lshlrev_b32_e32 v88, 16, v92
	v_and_b32_e32 v89, 0xffff0000, v92
	v_lshlrev_b32_e32 v90, 16, v93
	v_and_b32_e32 v91, 0xffff0000, v93
	v_lshlrev_b32_e32 v92, 16, v94
	v_and_b32_e32 v93, 0xffff0000, v94
	v_lshlrev_b32_e32 v94, 16, v95
	v_and_b32_e32 v95, 0xffff0000, v95
	v_pk_add_f32 v[84:85], v[84:85], v[88:89]
	v_pk_add_f32 v[88:89], v[82:83], v[94:95]
	v_pk_add_f32 v[82:83], v[80:81], v[92:93]
	v_pk_add_f32 v[86:87], v[86:87], v[90:91]
	v_cvt_pk_bf16_f32 v80, v84, v85
	s_nop 0
	v_cvt_pk_bf16_f32 v81, v86, v87
	v_cvt_pk_bf16_f32 v82, v82, v83
	v_cvt_pk_bf16_f32 v83, v88, v89
	flat_store_dwordx4 v[100:101], v[80:83] offset:256
	s_waitcnt vmcnt(12) lgkmcnt(0)
	s_nop 1
	v_mov_b32_e32 v80, v252
	v_mov_b32_e32 v81, v253
	v_mov_b32_e32 v82, v254
	v_mov_b32_e32 v83, v255
	v_lshlrev_b64 v[198:199], 11, v[142:143]
	v_lshl_add_u64 v[200:201], v[198:199], 0, v[146:147]
	v_lshl_add_u64 v[202:203], v[200:201], 0, s[46:47]
	v_lshlrev_b64 v[204:205], 1, v[202:203]
	v_lshl_add_u64 v[206:207], s[54:55], 0, v[204:205]
	global_load_dwordx4 v[252:255], v[206:207], off offset:256
	v_lshlrev_b32_e32 v84, 16, v80
	v_and_b32_e32 v85, 0xffff0000, v80
	v_lshlrev_b32_e32 v80, 16, v81
	v_and_b32_e32 v81, 0xffff0000, v81
	v_lshlrev_b32_e32 v86, 16, v82
	v_and_b32_e32 v87, 0xffff0000, v82
	v_lshlrev_b32_e32 v82, 16, v83
	v_and_b32_e32 v83, 0xffff0000, v83
	v_pk_add_f32 v[78:79], v[78:79], v[80:81]
	v_pk_add_f32 v[76:77], v[76:77], v[84:85]
	v_pk_add_f32 v[80:81], v[74:75], v[82:83]
	v_pk_add_f32 v[74:75], v[72:73], v[86:87]
	v_cvt_pk_bf16_f32 v72, v76, v77
	v_cvt_pk_bf16_f32 v73, v78, v79
	v_lshl_add_u64 v[84:85], s[56:57], 0, v[96:97]
	v_cvt_pk_bf16_f32 v74, v74, v75
	v_cvt_pk_bf16_f32 v75, v80, v81
	v_lshlrev_b64 v[80:81], 11, v[148:149]
	v_lshl_add_u64 v[80:81], v[80:81], 0, v[146:147]
	v_lshl_add_u64 v[80:81], v[80:81], 0, s[46:47]
	flat_store_dwordx4 v[84:85], v[72:75]
	v_lshlrev_b64 v[80:81], 1, v[80:81]
	v_lshl_add_u64 v[82:83], s[54:55], 0, v[80:81]
	s_waitcnt vmcnt(13) lgkmcnt(0)
	s_nop 1
	v_mov_b32_e32 v76, v228
	v_mov_b32_e32 v77, v229
	v_mov_b32_e32 v78, v230
	v_mov_b32_e32 v79, v231
	v_lshlrev_b64 v[198:199], 11, v[140:141]
	v_lshl_add_u64 v[200:201], v[198:199], 0, v[146:147]
	v_lshl_add_u64 v[202:203], v[200:201], 0, s[46:47]
	v_lshlrev_b64 v[204:205], 1, v[202:203]
	v_lshl_add_u64 v[206:207], s[54:55], 0, v[204:205]
	global_load_dwordx4 v[228:231], v[206:207], off
	v_lshlrev_b32_e32 v72, 16, v76
	v_and_b32_e32 v73, 0xffff0000, v76
	v_lshlrev_b32_e32 v74, 16, v77
	v_and_b32_e32 v75, 0xffff0000, v77
	v_lshlrev_b32_e32 v76, 16, v78
	v_and_b32_e32 v77, 0xffff0000, v78
	v_lshlrev_b32_e32 v78, 16, v79
	v_and_b32_e32 v79, 0xffff0000, v79
	v_pk_add_f32 v[68:69], v[68:69], v[72:73]
	v_pk_add_f32 v[72:73], v[66:67], v[78:79]
	v_pk_add_f32 v[66:67], v[64:65], v[76:77]
	v_pk_add_f32 v[70:71], v[70:71], v[74:75]
	v_cvt_pk_bf16_f32 v64, v68, v69
	s_nop 0
	v_cvt_pk_bf16_f32 v65, v70, v71
	v_cvt_pk_bf16_f32 v66, v66, v67
	v_cvt_pk_bf16_f32 v67, v72, v73
	flat_store_dwordx4 v[84:85], v[64:67] offset:256
	s_waitcnt vmcnt(13) lgkmcnt(0)
	s_nop 1
	v_mov_b32_e32 v64, v232
	v_mov_b32_e32 v65, v233
	v_mov_b32_e32 v66, v234
	v_mov_b32_e32 v67, v235
	v_lshlrev_b64 v[198:199], 11, v[140:141]
	v_lshl_add_u64 v[200:201], v[198:199], 0, v[146:147]
	v_lshl_add_u64 v[202:203], v[200:201], 0, s[46:47]
	v_lshlrev_b64 v[204:205], 1, v[202:203]
	v_lshl_add_u64 v[206:207], s[54:55], 0, v[204:205]
	global_load_dwordx4 v[232:235], v[206:207], off offset:256
	v_lshlrev_b32_e32 v68, 16, v64
	v_and_b32_e32 v69, 0xffff0000, v64
	v_lshlrev_b32_e32 v64, 16, v65
	v_and_b32_e32 v65, 0xffff0000, v65
	v_lshlrev_b32_e32 v70, 16, v66
	v_and_b32_e32 v71, 0xffff0000, v66
	v_lshlrev_b32_e32 v66, 16, v67
	v_and_b32_e32 v67, 0xffff0000, v67
	v_pk_add_f32 v[62:63], v[62:63], v[64:65]
	v_pk_add_f32 v[60:61], v[60:61], v[68:69]
	v_pk_add_f32 v[64:65], v[58:59], v[66:67]
	v_pk_add_f32 v[58:59], v[56:57], v[70:71]
	v_cvt_pk_bf16_f32 v56, v60, v61
	v_cvt_pk_bf16_f32 v57, v62, v63
	v_lshl_add_u64 v[68:69], s[56:57], 0, v[80:81]
	v_cvt_pk_bf16_f32 v58, v58, v59
	v_cvt_pk_bf16_f32 v59, v64, v65
	v_lshlrev_b64 v[64:65], 11, v[144:145]
	v_lshl_add_u64 v[64:65], v[64:65], 0, v[146:147]
	v_lshl_add_u64 v[64:65], v[64:65], 0, s[46:47]
	flat_store_dwordx4 v[68:69], v[56:59]
	v_lshlrev_b64 v[64:65], 1, v[64:65]
	v_lshl_add_u64 v[66:67], s[54:55], 0, v[64:65]
	s_waitcnt vmcnt(13) lgkmcnt(0)
	s_nop 1
	v_mov_b32_e32 v60, v236
	v_mov_b32_e32 v61, v237
	v_mov_b32_e32 v62, v238
	v_mov_b32_e32 v63, v239
	v_lshlrev_b32_e32 v56, 16, v60
	v_and_b32_e32 v57, 0xffff0000, v60
	v_lshlrev_b32_e32 v58, 16, v61
	v_and_b32_e32 v59, 0xffff0000, v61
	v_lshlrev_b32_e32 v60, 16, v62
	v_and_b32_e32 v61, 0xffff0000, v62
	v_lshlrev_b32_e32 v62, 16, v63
	v_and_b32_e32 v63, 0xffff0000, v63
	v_pk_add_f32 v[52:53], v[52:53], v[56:57]
	v_pk_add_f32 v[56:57], v[50:51], v[62:63]
	v_pk_add_f32 v[50:51], v[48:49], v[60:61]
	v_pk_add_f32 v[54:55], v[54:55], v[58:59]
	v_cvt_pk_bf16_f32 v48, v52, v53
	s_nop 0
	v_cvt_pk_bf16_f32 v49, v54, v55
	v_cvt_pk_bf16_f32 v50, v50, v51
	v_cvt_pk_bf16_f32 v51, v56, v57
	flat_store_dwordx4 v[68:69], v[48:51] offset:256
	s_waitcnt vmcnt(12) lgkmcnt(0)
	s_nop 1
	v_mov_b32_e32 v48, v240
	v_mov_b32_e32 v49, v241
	v_mov_b32_e32 v50, v242
	v_mov_b32_e32 v51, v243
	v_lshlrev_b32_e32 v52, 16, v48
	v_and_b32_e32 v53, 0xffff0000, v48
	v_lshlrev_b32_e32 v48, 16, v49
	v_and_b32_e32 v49, 0xffff0000, v49
	v_lshlrev_b32_e32 v54, 16, v50
	v_and_b32_e32 v55, 0xffff0000, v50
	v_lshlrev_b32_e32 v50, 16, v51
	v_and_b32_e32 v51, 0xffff0000, v51
	v_pk_add_f32 v[46:47], v[46:47], v[48:49]
	v_pk_add_f32 v[44:45], v[44:45], v[52:53]
	v_pk_add_f32 v[48:49], v[42:43], v[50:51]
	v_pk_add_f32 v[42:43], v[40:41], v[54:55]
	v_cvt_pk_bf16_f32 v40, v44, v45
	v_cvt_pk_bf16_f32 v41, v46, v47
	v_lshl_add_u64 v[52:53], s[56:57], 0, v[64:65]
	v_cvt_pk_bf16_f32 v42, v42, v43
	v_cvt_pk_bf16_f32 v43, v48, v49
	v_lshlrev_b64 v[48:49], 11, v[142:143]
	v_lshl_add_u64 v[48:49], v[48:49], 0, v[146:147]
	v_lshl_add_u64 v[48:49], v[48:49], 0, s[46:47]
	flat_store_dwordx4 v[52:53], v[40:43]
	v_lshlrev_b64 v[48:49], 1, v[48:49]
	v_lshl_add_u64 v[50:51], s[54:55], 0, v[48:49]
	s_waitcnt vmcnt(11) lgkmcnt(0)
	s_nop 1
	v_mov_b32_e32 v44, v244
	v_mov_b32_e32 v45, v245
	v_mov_b32_e32 v46, v246
	v_mov_b32_e32 v47, v247
	v_lshlrev_b32_e32 v40, 16, v44
	v_and_b32_e32 v41, 0xffff0000, v44
	v_lshlrev_b32_e32 v42, 16, v45
	v_and_b32_e32 v43, 0xffff0000, v45
	v_lshlrev_b32_e32 v44, 16, v46
	v_and_b32_e32 v45, 0xffff0000, v46
	v_lshlrev_b32_e32 v46, 16, v47
	v_and_b32_e32 v47, 0xffff0000, v47
	v_pk_add_f32 v[36:37], v[36:37], v[40:41]
	v_pk_add_f32 v[40:41], v[34:35], v[46:47]
	v_pk_add_f32 v[34:35], v[32:33], v[44:45]
	v_pk_add_f32 v[38:39], v[38:39], v[42:43]
	v_cvt_pk_bf16_f32 v32, v36, v37
	s_nop 0
	v_cvt_pk_bf16_f32 v33, v38, v39
	v_cvt_pk_bf16_f32 v34, v34, v35
	v_cvt_pk_bf16_f32 v35, v40, v41
	flat_store_dwordx4 v[52:53], v[32:35] offset:256
	s_waitcnt vmcnt(10) lgkmcnt(0)
	s_nop 1
	v_mov_b32_e32 v32, v248
	v_mov_b32_e32 v33, v249
	v_mov_b32_e32 v34, v250
	v_mov_b32_e32 v35, v251
	v_lshlrev_b32_e32 v36, 16, v32
	v_and_b32_e32 v37, 0xffff0000, v32
	v_lshlrev_b32_e32 v32, 16, v33
	v_and_b32_e32 v33, 0xffff0000, v33
	v_lshlrev_b32_e32 v38, 16, v34
	v_and_b32_e32 v39, 0xffff0000, v34
	v_lshlrev_b32_e32 v34, 16, v35
	v_and_b32_e32 v35, 0xffff0000, v35
	v_pk_add_f32 v[30:31], v[30:31], v[32:33]
	v_pk_add_f32 v[28:29], v[28:29], v[36:37]
	v_pk_add_f32 v[32:33], v[26:27], v[34:35]
	v_pk_add_f32 v[26:27], v[24:25], v[38:39]
	v_cvt_pk_bf16_f32 v24, v28, v29
	v_cvt_pk_bf16_f32 v25, v30, v31
	v_lshl_add_u64 v[36:37], s[56:57], 0, v[48:49]
	v_cvt_pk_bf16_f32 v26, v26, v27
	v_cvt_pk_bf16_f32 v27, v32, v33
	v_lshlrev_b64 v[32:33], 11, v[140:141]
	v_lshl_add_u64 v[32:33], v[32:33], 0, v[146:147]
	v_lshl_add_u64 v[32:33], v[32:33], 0, s[46:47]
	flat_store_dwordx4 v[36:37], v[24:27]
	v_lshlrev_b64 v[32:33], 1, v[32:33]
	v_lshl_add_u64 v[34:35], s[54:55], 0, v[32:33]
	s_waitcnt vmcnt(9) lgkmcnt(0)
	s_nop 1
	v_mov_b32_e32 v28, v252
	v_mov_b32_e32 v29, v253
	v_mov_b32_e32 v30, v254
	v_mov_b32_e32 v31, v255
	v_lshlrev_b32_e32 v24, 16, v28
	v_and_b32_e32 v25, 0xffff0000, v28
	v_lshlrev_b32_e32 v26, 16, v29
	v_and_b32_e32 v27, 0xffff0000, v29
	v_lshlrev_b32_e32 v28, 16, v30
	v_and_b32_e32 v29, 0xffff0000, v30
	v_lshlrev_b32_e32 v30, 16, v31
	v_and_b32_e32 v31, 0xffff0000, v31
	v_pk_add_f32 v[20:21], v[20:21], v[24:25]
	v_pk_add_f32 v[24:25], v[18:19], v[30:31]
	v_pk_add_f32 v[18:19], v[16:17], v[28:29]
	v_pk_add_f32 v[22:23], v[22:23], v[26:27]
	v_cvt_pk_bf16_f32 v16, v20, v21
	s_nop 0
	v_cvt_pk_bf16_f32 v17, v22, v23
	v_cvt_pk_bf16_f32 v18, v18, v19
	v_cvt_pk_bf16_f32 v19, v24, v25
	flat_store_dwordx4 v[36:37], v[16:19] offset:256
	s_waitcnt vmcnt(8) lgkmcnt(0)
	s_nop 1
	v_mov_b32_e32 v16, v228
	v_mov_b32_e32 v17, v229
	v_mov_b32_e32 v18, v230
	v_mov_b32_e32 v19, v231
	v_lshlrev_b32_e32 v20, 16, v16
	v_and_b32_e32 v21, 0xffff0000, v16
	v_lshlrev_b32_e32 v16, 16, v17
	v_and_b32_e32 v17, 0xffff0000, v17
	v_lshlrev_b32_e32 v22, 16, v18
	v_and_b32_e32 v23, 0xffff0000, v18
	v_lshlrev_b32_e32 v18, 16, v19
	v_and_b32_e32 v19, 0xffff0000, v19
	v_pk_add_f32 v[14:15], v[14:15], v[16:17]
	v_pk_add_f32 v[12:13], v[12:13], v[20:21]
	v_pk_add_f32 v[16:17], v[10:11], v[18:19]
	v_pk_add_f32 v[10:11], v[8:9], v[22:23]
	v_cvt_pk_bf16_f32 v8, v12, v13
	v_cvt_pk_bf16_f32 v9, v14, v15
	s_nop 0
	v_cvt_pk_bf16_f32 v10, v10, v11
	v_cvt_pk_bf16_f32 v11, v16, v17
	v_lshl_add_u64 v[16:17], s[56:57], 0, v[32:33]
	flat_store_dwordx4 v[16:17], v[8:11]
	s_waitcnt vmcnt(7) lgkmcnt(0)
	s_nop 1
	v_mov_b32_e32 v12, v232
	v_mov_b32_e32 v13, v233
	v_mov_b32_e32 v14, v234
	v_mov_b32_e32 v15, v235
	s_nop 0
	v_lshlrev_b32_e32 v8, 16, v12
	v_and_b32_e32 v9, 0xffff0000, v12
	v_lshlrev_b32_e32 v10, 16, v13
	v_and_b32_e32 v11, 0xffff0000, v13
	v_lshlrev_b32_e32 v12, 16, v14
	v_and_b32_e32 v13, 0xffff0000, v14
	v_lshlrev_b32_e32 v14, 16, v15
	v_and_b32_e32 v15, 0xffff0000, v15
	v_pk_add_f32 v[4:5], v[4:5], v[8:9]
	v_pk_add_f32 v[8:9], v[2:3], v[14:15]
	v_pk_add_f32 v[2:3], v[0:1], v[12:13]
	v_pk_add_f32 v[6:7], v[6:7], v[10:11]
	v_cvt_pk_bf16_f32 v0, v4, v5
	s_nop 0
	v_cvt_pk_bf16_f32 v1, v6, v7
	v_cvt_pk_bf16_f32 v2, v2, v3
	v_cvt_pk_bf16_f32 v3, v8, v9
	flat_store_dwordx4 v[16:17], v[0:3] offset:256

.LBB0_1227:
	v_lshl_add_u32 v146, v165, 3, s72
	s_ashr_i32 s51, s50, 31
	v_ashrrev_i32_e32 v147, 31, v146
	v_lshlrev_b64 v[156:157], 11, v[156:157]
	s_lshl_b64 s[50:51], s[50:51], 12
	v_lshl_add_u64 v[156:157], v[156:157], 0, v[146:147]
	s_add_u32 s50, s67, s50
	s_addc_u32 s51, s68, s51
	v_lshlrev_b64 v[156:157], 1, v[156:157]
	v_lshl_add_u64 v[166:167], s[50:51], 0, v[156:157]
	s_lshl_b64 s[52:53], s[48:49], 1
	v_lshl_add_u64 v[170:171], v[166:167], 0, s[52:53]
	flat_load_dwordx4 v[166:169], v[170:171]
	s_add_u32 s48, s50, s52
	s_addc_u32 s49, s51, s53
	v_lshl_add_u64 v[156:157], s[48:49], 0, v[156:157]
	v_ashrrev_i32_e32 v155, 31, v154
	v_lshlrev_b64 v[154:155], 11, v[154:155]
	v_lshl_add_u64 v[154:155], v[154:155], 0, v[146:147]
	v_lshlrev_b64 v[154:155], 1, v[154:155]
	v_ashrrev_i32_e32 v153, 31, v152
	v_ashrrev_i32_e32 v151, 31, v150
	v_ashrrev_i32_e32 v149, 31, v148
	v_ashrrev_i32_e32 v145, 31, v144
	v_ashrrev_i32_e32 v143, 31, v142
	v_ashrrev_i32_e32 v141, 31, v140
	global_load_dwordx4 v[232:235], v[156:157], off offset:256
	v_lshl_add_u64 v[198:199], s[50:51], 0, v[154:155]
	v_lshl_add_u64 v[200:201], v[198:199], 0, s[52:53]
	global_load_dwordx4 v[236:239], v[200:201], off
	v_lshl_add_u64 v[198:199], s[48:49], 0, v[154:155]
	global_load_dwordx4 v[240:243], v[198:199], off offset:256
	v_lshlrev_b64 v[198:199], 11, v[152:153]
	v_lshl_add_u64 v[200:201], v[198:199], 0, v[146:147]
	v_lshlrev_b64 v[202:203], 1, v[200:201]
	v_lshl_add_u64 v[204:205], s[50:51], 0, v[202:203]
	v_lshl_add_u64 v[206:207], v[204:205], 0, s[52:53]
	global_load_dwordx4 v[244:247], v[206:207], off
	v_lshlrev_b64 v[198:199], 11, v[152:153]
	v_lshl_add_u64 v[200:201], v[198:199], 0, v[146:147]
	v_lshlrev_b64 v[202:203], 1, v[200:201]
	v_lshl_add_u64 v[204:205], s[48:49], 0, v[202:203]
	global_load_dwordx4 v[248:251], v[204:205], off offset:256
	v_lshlrev_b64 v[198:199], 11, v[150:151]
	v_lshl_add_u64 v[200:201], v[198:199], 0, v[146:147]
	v_lshlrev_b64 v[202:203], 1, v[200:201]
	v_lshl_add_u64 v[204:205], s[50:51], 0, v[202:203]
	v_lshl_add_u64 v[206:207], v[204:205], 0, s[52:53]
	global_load_dwordx4 v[252:255], v[206:207], off
	s_waitcnt vmcnt(6) lgkmcnt(0)
	v_lshlrev_b64 v[198:199], 11, v[150:151]
	v_lshl_add_u64 v[200:201], v[198:199], 0, v[146:147]
	v_lshlrev_b64 v[202:203], 1, v[200:201]
	v_lshl_add_u64 v[204:205], s[48:49], 0, v[202:203]
	global_load_dwordx4 v[228:231], v[204:205], off offset:256
	v_lshlrev_b32_e32 v172, 16, v166
	v_and_b32_e32 v173, 0xffff0000, v166
	v_lshlrev_b32_e32 v166, 16, v167
	v_and_b32_e32 v167, 0xffff0000, v167
	v_lshlrev_b32_e32 v174, 16, v168
	v_and_b32_e32 v175, 0xffff0000, v168
	v_lshlrev_b32_e32 v168, 16, v169
	v_and_b32_e32 v169, 0xffff0000, v169
	v_pk_add_f32 v[126:127], v[126:127], v[166:167]
	v_pk_add_f32 v[124:125], v[124:125], v[172:173]
	v_pk_add_f32 v[166:167], v[122:123], v[168:169]
	v_pk_add_f32 v[122:123], v[120:121], v[174:175]
	v_cvt_pk_bf16_f32 v120, v124, v125
	v_cvt_pk_bf16_f32 v121, v126, v127
	s_nop 0
	v_cvt_pk_bf16_f32 v122, v122, v123
	v_cvt_pk_bf16_f32 v123, v166, v167
	v_lshl_add_u64 v[166:167], s[50:51], 0, v[154:155]
	flat_store_dwordx4 v[170:171], v[120:123]
	v_lshl_add_u64 v[166:167], v[166:167], 0, s[52:53]
	s_waitcnt vmcnt(7) lgkmcnt(0)
	s_nop 1
	v_mov_b32_e32 v124, v232
	v_mov_b32_e32 v125, v233
	v_mov_b32_e32 v126, v234
	v_mov_b32_e32 v127, v235
	v_lshlrev_b64 v[198:199], 11, v[148:149]
	v_lshl_add_u64 v[200:201], v[198:199], 0, v[146:147]
	v_lshlrev_b64 v[202:203], 1, v[200:201]
	v_lshl_add_u64 v[204:205], s[50:51], 0, v[202:203]
	v_lshl_add_u64 v[206:207], v[204:205], 0, s[52:53]
	global_load_dwordx4 v[232:235], v[206:207], off
	v_lshlrev_b32_e32 v120, 16, v124
	v_and_b32_e32 v121, 0xffff0000, v124
	v_lshlrev_b32_e32 v122, 16, v125
	v_and_b32_e32 v123, 0xffff0000, v125
	v_lshlrev_b32_e32 v124, 16, v126
	v_and_b32_e32 v125, 0xffff0000, v126
	v_lshlrev_b32_e32 v126, 16, v127
	v_and_b32_e32 v127, 0xffff0000, v127
	v_pk_add_f32 v[116:117], v[116:117], v[120:121]
	v_pk_add_f32 v[120:121], v[114:115], v[126:127]
	v_pk_add_f32 v[114:115], v[112:113], v[124:125]
	v_pk_add_f32 v[118:119], v[118:119], v[122:123]
	v_cvt_pk_bf16_f32 v112, v116, v117
	v_lshl_add_u64 v[116:117], s[48:49], 0, v[154:155]
	v_cvt_pk_bf16_f32 v113, v118, v119
	v_cvt_pk_bf16_f32 v114, v114, v115
	v_cvt_pk_bf16_f32 v115, v120, v121
	flat_store_dwordx4 v[156:157], v[112:115] offset:256
	s_waitcnt vmcnt(8) lgkmcnt(0)
	s_nop 1
	v_mov_b32_e32 v112, v236
	v_mov_b32_e32 v113, v237
	v_mov_b32_e32 v114, v238
	v_mov_b32_e32 v115, v239
	v_lshlrev_b64 v[198:199], 11, v[148:149]
	v_lshl_add_u64 v[200:201], v[198:199], 0, v[146:147]
	v_lshlrev_b64 v[202:203], 1, v[200:201]
	v_lshl_add_u64 v[204:205], s[48:49], 0, v[202:203]
	global_load_dwordx4 v[236:239], v[204:205], off offset:256
	v_lshlrev_b32_e32 v118, 16, v112
	v_and_b32_e32 v119, 0xffff0000, v112
	v_lshlrev_b32_e32 v112, 16, v113
	v_and_b32_e32 v113, 0xffff0000, v113
	v_lshlrev_b32_e32 v120, 16, v114
	v_and_b32_e32 v121, 0xffff0000, v114
	v_lshlrev_b32_e32 v114, 16, v115
	v_and_b32_e32 v115, 0xffff0000, v115
	v_pk_add_f32 v[110:111], v[110:111], v[112:113]
	v_pk_add_f32 v[108:109], v[108:109], v[118:119]
	v_pk_add_f32 v[112:113], v[106:107], v[114:115]
	v_pk_add_f32 v[106:107], v[104:105], v[120:121]
	v_cvt_pk_bf16_f32 v104, v108, v109
	v_cvt_pk_bf16_f32 v105, v110, v111
	s_nop 0
	v_cvt_pk_bf16_f32 v106, v106, v107
	v_cvt_pk_bf16_f32 v107, v112, v113
	v_lshlrev_b64 v[112:113], 11, v[152:153]
	v_lshl_add_u64 v[112:113], v[112:113], 0, v[146:147]
	v_lshlrev_b64 v[112:113], 1, v[112:113]
	flat_store_dwordx4 v[166:167], v[104:107]
	v_lshl_add_u64 v[114:115], s[50:51], 0, v[112:113]
	v_lshl_add_u64 v[114:115], v[114:115], 0, s[52:53]
	s_waitcnt vmcnt(9) lgkmcnt(0)
	s_nop 1
	v_mov_b32_e32 v108, v240
	v_mov_b32_e32 v109, v241
	v_mov_b32_e32 v110, v242
	v_mov_b32_e32 v111, v243
	v_lshlrev_b64 v[198:199], 11, v[144:145]
	v_lshl_add_u64 v[200:201], v[198:199], 0, v[146:147]
	v_lshlrev_b64 v[202:203], 1, v[200:201]
	v_lshl_add_u64 v[204:205], s[50:51], 0, v[202:203]
	v_lshl_add_u64 v[206:207], v[204:205], 0, s[52:53]
	global_load_dwordx4 v[240:243], v[206:207], off
	v_lshlrev_b32_e32 v104, 16, v108
	v_and_b32_e32 v105, 0xffff0000, v108
	v_lshlrev_b32_e32 v106, 16, v109
	v_and_b32_e32 v107, 0xffff0000, v109
	v_lshlrev_b32_e32 v108, 16, v110
	v_and_b32_e32 v109, 0xffff0000, v110
	v_lshlrev_b32_e32 v110, 16, v111
	v_and_b32_e32 v111, 0xffff0000, v111
	v_pk_add_f32 v[100:101], v[100:101], v[104:105]
	v_pk_add_f32 v[104:105], v[98:99], v[110:111]
	v_pk_add_f32 v[98:99], v[96:97], v[108:109]
	v_pk_add_f32 v[102:103], v[102:103], v[106:107]
	v_cvt_pk_bf16_f32 v96, v100, v101
	v_lshl_add_u64 v[100:101], s[48:49], 0, v[112:113]
	v_cvt_pk_bf16_f32 v97, v102, v103
	v_cvt_pk_bf16_f32 v98, v98, v99
	v_cvt_pk_bf16_f32 v99, v104, v105
	flat_store_dwordx4 v[116:117], v[96:99] offset:256
	s_waitcnt vmcnt(10) lgkmcnt(0)
	s_nop 1
	v_mov_b32_e32 v96, v244
	v_mov_b32_e32 v97, v245
	v_mov_b32_e32 v98, v246
	v_mov_b32_e32 v99, v247
	v_lshlrev_b64 v[198:199], 11, v[144:145]
	v_lshl_add_u64 v[200:201], v[198:199], 0, v[146:147]
	v_lshlrev_b64 v[202:203], 1, v[200:201]
	v_lshl_add_u64 v[204:205], s[48:49], 0, v[202:203]
	global_load_dwordx4 v[244:247], v[204:205], off offset:256
	v_lshlrev_b32_e32 v102, 16, v96
	v_and_b32_e32 v103, 0xffff0000, v96
	v_lshlrev_b32_e32 v96, 16, v97
	v_and_b32_e32 v97, 0xffff0000, v97
	v_lshlrev_b32_e32 v104, 16, v98
	v_and_b32_e32 v105, 0xffff0000, v98
	v_lshlrev_b32_e32 v98, 16, v99
	v_and_b32_e32 v99, 0xffff0000, v99
	v_pk_add_f32 v[94:95], v[94:95], v[96:97]
	v_pk_add_f32 v[92:93], v[92:93], v[102:103]
	v_pk_add_f32 v[96:97], v[90:91], v[98:99]
	v_pk_add_f32 v[90:91], v[88:89], v[104:105]
	v_cvt_pk_bf16_f32 v88, v92, v93
	v_cvt_pk_bf16_f32 v89, v94, v95
	s_nop 0
	v_cvt_pk_bf16_f32 v90, v90, v91
	v_cvt_pk_bf16_f32 v91, v96, v97
	v_lshlrev_b64 v[96:97], 11, v[150:151]
	v_lshl_add_u64 v[96:97], v[96:97], 0, v[146:147]
	v_lshlrev_b64 v[96:97], 1, v[96:97]
	flat_store_dwordx4 v[114:115], v[88:91]
	v_lshl_add_u64 v[98:99], s[50:51], 0, v[96:97]
	v_lshl_add_u64 v[98:99], v[98:99], 0, s[52:53]
	s_waitcnt vmcnt(11) lgkmcnt(0)
	s_nop 1
	v_mov_b32_e32 v92, v248
	v_mov_b32_e32 v93, v249
	v_mov_b32_e32 v94, v250
	v_mov_b32_e32 v95, v251
	v_lshlrev_b64 v[198:199], 11, v[142:143]
	v_lshl_add_u64 v[200:201], v[198:199], 0, v[146:147]
	v_lshlrev_b64 v[202:203], 1, v[200:201]
	v_lshl_add_u64 v[204:205], s[50:51], 0, v[202:203]
	v_lshl_add_u64 v[206:207], v[204:205], 0, s[52:53]
	global_load_dwordx4 v[248:251], v[206:207], off
	v_lshlrev_b32_e32 v88, 16, v92
	v_and_b32_e32 v89, 0xffff0000, v92
	v_lshlrev_b32_e32 v90, 16, v93
	v_and_b32_e32 v91, 0xffff0000, v93
	v_lshlrev_b32_e32 v92, 16, v94
	v_and_b32_e32 v93, 0xffff0000, v94
	v_lshlrev_b32_e32 v94, 16, v95
	v_and_b32_e32 v95, 0xffff0000, v95
	v_pk_add_f32 v[84:85], v[84:85], v[88:89]
	v_pk_add_f32 v[88:89], v[82:83], v[94:95]
	v_pk_add_f32 v[82:83], v[80:81], v[92:93]
	v_pk_add_f32 v[86:87], v[86:87], v[90:91]
	v_cvt_pk_bf16_f32 v80, v84, v85
	v_lshl_add_u64 v[84:85], s[48:49], 0, v[96:97]
	v_cvt_pk_bf16_f32 v81, v86, v87
	v_cvt_pk_bf16_f32 v82, v82, v83
	v_cvt_pk_bf16_f32 v83, v88, v89
	flat_store_dwordx4 v[100:101], v[80:83] offset:256
	s_waitcnt vmcnt(12) lgkmcnt(0)
	s_nop 1
	v_mov_b32_e32 v80, v252
	v_mov_b32_e32 v81, v253
	v_mov_b32_e32 v82, v254
	v_mov_b32_e32 v83, v255
	v_lshlrev_b64 v[198:199], 11, v[142:143]
	v_lshl_add_u64 v[200:201], v[198:199], 0, v[146:147]
	v_lshlrev_b64 v[202:203], 1, v[200:201]
	v_lshl_add_u64 v[204:205], s[48:49], 0, v[202:203]
	global_load_dwordx4 v[252:255], v[204:205], off offset:256
	v_lshlrev_b32_e32 v86, 16, v80
	v_and_b32_e32 v87, 0xffff0000, v80
	v_lshlrev_b32_e32 v80, 16, v81
	v_and_b32_e32 v81, 0xffff0000, v81
	v_lshlrev_b32_e32 v88, 16, v82
	v_and_b32_e32 v89, 0xffff0000, v82
	v_lshlrev_b32_e32 v82, 16, v83
	v_and_b32_e32 v83, 0xffff0000, v83
	v_pk_add_f32 v[78:79], v[78:79], v[80:81]
	v_pk_add_f32 v[76:77], v[76:77], v[86:87]
	v_pk_add_f32 v[80:81], v[74:75], v[82:83]
	v_pk_add_f32 v[74:75], v[72:73], v[88:89]
	v_cvt_pk_bf16_f32 v72, v76, v77
	v_cvt_pk_bf16_f32 v73, v78, v79
	s_nop 0
	v_cvt_pk_bf16_f32 v74, v74, v75
	v_cvt_pk_bf16_f32 v75, v80, v81
	v_lshlrev_b64 v[80:81], 11, v[148:149]
	v_lshl_add_u64 v[80:81], v[80:81], 0, v[146:147]
	v_lshlrev_b64 v[80:81], 1, v[80:81]
	flat_store_dwordx4 v[98:99], v[72:75]
	v_lshl_add_u64 v[82:83], s[50:51], 0, v[80:81]
	v_lshl_add_u64 v[82:83], v[82:83], 0, s[52:53]
	s_waitcnt vmcnt(13) lgkmcnt(0)
	s_nop 1
	v_mov_b32_e32 v76, v228
	v_mov_b32_e32 v77, v229
	v_mov_b32_e32 v78, v230
	v_mov_b32_e32 v79, v231
	v_lshlrev_b64 v[198:199], 11, v[140:141]
	v_lshl_add_u64 v[200:201], v[198:199], 0, v[146:147]
	v_lshlrev_b64 v[202:203], 1, v[200:201]
	v_lshl_add_u64 v[204:205], s[50:51], 0, v[202:203]
	v_lshl_add_u64 v[206:207], v[204:205], 0, s[52:53]
	global_load_dwordx4 v[228:231], v[206:207], off
	v_lshlrev_b32_e32 v72, 16, v76
	v_and_b32_e32 v73, 0xffff0000, v76
	v_lshlrev_b32_e32 v74, 16, v77
	v_and_b32_e32 v75, 0xffff0000, v77
	v_lshlrev_b32_e32 v76, 16, v78
	v_and_b32_e32 v77, 0xffff0000, v78
	v_lshlrev_b32_e32 v78, 16, v79
	v_and_b32_e32 v79, 0xffff0000, v79
	v_pk_add_f32 v[68:69], v[68:69], v[72:73]
	v_pk_add_f32 v[72:73], v[66:67], v[78:79]
	v_pk_add_f32 v[66:67], v[64:65], v[76:77]
	v_pk_add_f32 v[70:71], v[70:71], v[74:75]
	v_cvt_pk_bf16_f32 v64, v68, v69
	v_lshl_add_u64 v[68:69], s[48:49], 0, v[80:81]
	v_cvt_pk_bf16_f32 v65, v70, v71
	v_cvt_pk_bf16_f32 v66, v66, v67
	v_cvt_pk_bf16_f32 v67, v72, v73
	flat_store_dwordx4 v[84:85], v[64:67] offset:256
	s_waitcnt vmcnt(13) lgkmcnt(0)
	s_nop 1
	v_mov_b32_e32 v64, v232
	v_mov_b32_e32 v65, v233
	v_mov_b32_e32 v66, v234
	v_mov_b32_e32 v67, v235
	v_lshlrev_b64 v[198:199], 11, v[140:141]
	v_lshl_add_u64 v[200:201], v[198:199], 0, v[146:147]
	v_lshlrev_b64 v[202:203], 1, v[200:201]
	v_lshl_add_u64 v[204:205], s[48:49], 0, v[202:203]
	global_load_dwordx4 v[232:235], v[204:205], off offset:256
	v_lshlrev_b32_e32 v70, 16, v64
	v_and_b32_e32 v71, 0xffff0000, v64
	v_lshlrev_b32_e32 v64, 16, v65
	v_and_b32_e32 v65, 0xffff0000, v65
	v_lshlrev_b32_e32 v72, 16, v66
	v_and_b32_e32 v73, 0xffff0000, v66
	v_lshlrev_b32_e32 v66, 16, v67
	v_and_b32_e32 v67, 0xffff0000, v67
	v_pk_add_f32 v[62:63], v[62:63], v[64:65]
	v_pk_add_f32 v[60:61], v[60:61], v[70:71]
	v_pk_add_f32 v[64:65], v[58:59], v[66:67]
	v_pk_add_f32 v[58:59], v[56:57], v[72:73]
	v_cvt_pk_bf16_f32 v56, v60, v61
	v_cvt_pk_bf16_f32 v57, v62, v63
	s_nop 0
	v_cvt_pk_bf16_f32 v58, v58, v59
	v_cvt_pk_bf16_f32 v59, v64, v65
	v_lshlrev_b64 v[64:65], 11, v[144:145]
	v_lshl_add_u64 v[64:65], v[64:65], 0, v[146:147]
	v_lshlrev_b64 v[64:65], 1, v[64:65]
	flat_store_dwordx4 v[82:83], v[56:59]
	v_lshl_add_u64 v[66:67], s[50:51], 0, v[64:65]
	v_lshl_add_u64 v[66:67], v[66:67], 0, s[52:53]
	s_waitcnt vmcnt(13) lgkmcnt(0)
	s_nop 1
	v_mov_b32_e32 v60, v236
	v_mov_b32_e32 v61, v237
	v_mov_b32_e32 v62, v238
	v_mov_b32_e32 v63, v239
	v_lshlrev_b32_e32 v56, 16, v60
	v_and_b32_e32 v57, 0xffff0000, v60
	v_lshlrev_b32_e32 v58, 16, v61
	v_and_b32_e32 v59, 0xffff0000, v61
	v_lshlrev_b32_e32 v60, 16, v62
	v_and_b32_e32 v61, 0xffff0000, v62
	v_lshlrev_b32_e32 v62, 16, v63
	v_and_b32_e32 v63, 0xffff0000, v63
	v_pk_add_f32 v[52:53], v[52:53], v[56:57]
	v_pk_add_f32 v[56:57], v[50:51], v[62:63]
	v_pk_add_f32 v[50:51], v[48:49], v[60:61]
	v_pk_add_f32 v[54:55], v[54:55], v[58:59]
	v_cvt_pk_bf16_f32 v48, v52, v53
	v_lshl_add_u64 v[52:53], s[48:49], 0, v[64:65]
	v_cvt_pk_bf16_f32 v49, v54, v55
	v_cvt_pk_bf16_f32 v50, v50, v51
	v_cvt_pk_bf16_f32 v51, v56, v57
	flat_store_dwordx4 v[68:69], v[48:51] offset:256
	s_waitcnt vmcnt(12) lgkmcnt(0)
	s_nop 1
	v_mov_b32_e32 v48, v240
	v_mov_b32_e32 v49, v241
	v_mov_b32_e32 v50, v242
	v_mov_b32_e32 v51, v243
	v_lshlrev_b32_e32 v54, 16, v48
	v_and_b32_e32 v55, 0xffff0000, v48
	v_lshlrev_b32_e32 v48, 16, v49
	v_and_b32_e32 v49, 0xffff0000, v49
	v_lshlrev_b32_e32 v56, 16, v50
	v_and_b32_e32 v57, 0xffff0000, v50
	v_lshlrev_b32_e32 v50, 16, v51
	v_and_b32_e32 v51, 0xffff0000, v51
	v_pk_add_f32 v[46:47], v[46:47], v[48:49]
	v_pk_add_f32 v[44:45], v[44:45], v[54:55]
	v_pk_add_f32 v[48:49], v[42:43], v[50:51]
	v_pk_add_f32 v[42:43], v[40:41], v[56:57]
	v_cvt_pk_bf16_f32 v40, v44, v45
	v_cvt_pk_bf16_f32 v41, v46, v47
	s_nop 0
	v_cvt_pk_bf16_f32 v42, v42, v43
	v_cvt_pk_bf16_f32 v43, v48, v49
	v_lshlrev_b64 v[48:49], 11, v[142:143]
	v_lshl_add_u64 v[48:49], v[48:49], 0, v[146:147]
	v_lshlrev_b64 v[48:49], 1, v[48:49]
	flat_store_dwordx4 v[66:67], v[40:43]
	v_lshl_add_u64 v[50:51], s[50:51], 0, v[48:49]
	v_lshl_add_u64 v[50:51], v[50:51], 0, s[52:53]
	s_waitcnt vmcnt(11) lgkmcnt(0)
	s_nop 1
	v_mov_b32_e32 v44, v244
	v_mov_b32_e32 v45, v245
	v_mov_b32_e32 v46, v246
	v_mov_b32_e32 v47, v247
	v_lshlrev_b32_e32 v40, 16, v44
	v_and_b32_e32 v41, 0xffff0000, v44
	v_lshlrev_b32_e32 v42, 16, v45
	v_and_b32_e32 v43, 0xffff0000, v45
	v_lshlrev_b32_e32 v44, 16, v46
	v_and_b32_e32 v45, 0xffff0000, v46
	v_lshlrev_b32_e32 v46, 16, v47
	v_and_b32_e32 v47, 0xffff0000, v47
	v_pk_add_f32 v[36:37], v[36:37], v[40:41]
	v_pk_add_f32 v[40:41], v[34:35], v[46:47]
	v_pk_add_f32 v[34:35], v[32:33], v[44:45]
	v_pk_add_f32 v[38:39], v[38:39], v[42:43]
	v_cvt_pk_bf16_f32 v32, v36, v37
	v_lshl_add_u64 v[36:37], s[48:49], 0, v[48:49]
	v_cvt_pk_bf16_f32 v33, v38, v39
	v_cvt_pk_bf16_f32 v34, v34, v35
	v_cvt_pk_bf16_f32 v35, v40, v41
	flat_store_dwordx4 v[52:53], v[32:35] offset:256
	s_waitcnt vmcnt(10) lgkmcnt(0)
	s_nop 1
	v_mov_b32_e32 v32, v248
	v_mov_b32_e32 v33, v249
	v_mov_b32_e32 v34, v250
	v_mov_b32_e32 v35, v251
	v_lshlrev_b32_e32 v38, 16, v32
	v_and_b32_e32 v39, 0xffff0000, v32
	v_lshlrev_b32_e32 v32, 16, v33
	v_and_b32_e32 v33, 0xffff0000, v33
	v_lshlrev_b32_e32 v40, 16, v34
	v_and_b32_e32 v41, 0xffff0000, v34
	v_lshlrev_b32_e32 v34, 16, v35
	v_and_b32_e32 v35, 0xffff0000, v35
	v_pk_add_f32 v[30:31], v[30:31], v[32:33]
	v_pk_add_f32 v[28:29], v[28:29], v[38:39]
	v_pk_add_f32 v[32:33], v[26:27], v[34:35]
	v_pk_add_f32 v[26:27], v[24:25], v[40:41]
	v_cvt_pk_bf16_f32 v24, v28, v29
	v_cvt_pk_bf16_f32 v25, v30, v31
	s_nop 0
	v_cvt_pk_bf16_f32 v26, v26, v27
	v_cvt_pk_bf16_f32 v27, v32, v33
	v_lshlrev_b64 v[32:33], 11, v[140:141]
	v_lshl_add_u64 v[32:33], v[32:33], 0, v[146:147]
	v_lshlrev_b64 v[32:33], 1, v[32:33]
	flat_store_dwordx4 v[50:51], v[24:27]
	v_lshl_add_u64 v[34:35], s[50:51], 0, v[32:33]
	v_lshl_add_u64 v[34:35], v[34:35], 0, s[52:53]
	s_waitcnt vmcnt(9) lgkmcnt(0)
	s_nop 1
	v_mov_b32_e32 v28, v252
	v_mov_b32_e32 v29, v253
	v_mov_b32_e32 v30, v254
	v_mov_b32_e32 v31, v255
	v_lshlrev_b32_e32 v24, 16, v28
	v_and_b32_e32 v25, 0xffff0000, v28
	v_lshlrev_b32_e32 v26, 16, v29
	v_and_b32_e32 v27, 0xffff0000, v29
	v_lshlrev_b32_e32 v28, 16, v30
	v_and_b32_e32 v29, 0xffff0000, v30
	v_lshlrev_b32_e32 v30, 16, v31
	v_and_b32_e32 v31, 0xffff0000, v31
	v_pk_add_f32 v[20:21], v[20:21], v[24:25]
	v_pk_add_f32 v[24:25], v[18:19], v[30:31]
	v_pk_add_f32 v[18:19], v[16:17], v[28:29]
	v_pk_add_f32 v[22:23], v[22:23], v[26:27]
	v_cvt_pk_bf16_f32 v16, v20, v21
	v_lshl_add_u64 v[20:21], s[48:49], 0, v[32:33]
	v_cvt_pk_bf16_f32 v17, v22, v23
	v_cvt_pk_bf16_f32 v18, v18, v19
	v_cvt_pk_bf16_f32 v19, v24, v25
	flat_store_dwordx4 v[36:37], v[16:19] offset:256
	s_waitcnt vmcnt(8) lgkmcnt(0)
	s_nop 1
	v_mov_b32_e32 v16, v228
	v_mov_b32_e32 v17, v229
	v_mov_b32_e32 v18, v230
	v_mov_b32_e32 v19, v231
	v_lshlrev_b32_e32 v22, 16, v16
	v_and_b32_e32 v23, 0xffff0000, v16
	v_lshlrev_b32_e32 v16, 16, v17
	v_and_b32_e32 v17, 0xffff0000, v17
	v_lshlrev_b32_e32 v24, 16, v18
	v_and_b32_e32 v25, 0xffff0000, v18
	v_lshlrev_b32_e32 v18, 16, v19
	v_and_b32_e32 v19, 0xffff0000, v19
	v_pk_add_f32 v[14:15], v[14:15], v[16:17]
	v_pk_add_f32 v[12:13], v[12:13], v[22:23]
	v_pk_add_f32 v[16:17], v[10:11], v[18:19]
	v_pk_add_f32 v[10:11], v[8:9], v[24:25]
	v_cvt_pk_bf16_f32 v8, v12, v13
	v_cvt_pk_bf16_f32 v9, v14, v15
	s_nop 0
	v_cvt_pk_bf16_f32 v10, v10, v11
	v_cvt_pk_bf16_f32 v11, v16, v17
	s_nop 0
	flat_store_dwordx4 v[34:35], v[8:11]
	s_waitcnt vmcnt(7) lgkmcnt(0)
	s_nop 1
	v_mov_b32_e32 v12, v232
	v_mov_b32_e32 v13, v233
	v_mov_b32_e32 v14, v234
	v_mov_b32_e32 v15, v235
	s_nop 0
	v_lshlrev_b32_e32 v8, 16, v12
	v_and_b32_e32 v9, 0xffff0000, v12
	v_lshlrev_b32_e32 v10, 16, v13
	v_and_b32_e32 v11, 0xffff0000, v13
	v_lshlrev_b32_e32 v12, 16, v14
	v_and_b32_e32 v13, 0xffff0000, v14
	v_lshlrev_b32_e32 v14, 16, v15
	v_and_b32_e32 v15, 0xffff0000, v15
	v_pk_add_f32 v[4:5], v[4:5], v[8:9]
	v_pk_add_f32 v[8:9], v[2:3], v[14:15]
	v_pk_add_f32 v[2:3], v[0:1], v[12:13]
	v_pk_add_f32 v[6:7], v[6:7], v[10:11]
	v_cvt_pk_bf16_f32 v0, v4, v5
	s_nop 0
	v_cvt_pk_bf16_f32 v1, v6, v7
	v_cvt_pk_bf16_f32 v2, v2, v3
	v_cvt_pk_bf16_f32 v3, v8, v9
	flat_store_dwordx4 v[20:21], v[0:3] offset:256
